# attention prologue: per-layer gain vectors prefetched before the PRE-done signal instead of a serial pointer/load chain at phase start
# speedup vs baseline: 1.0006x; 1.0006x over previous
.LBB0_163:
	v_readlane_b32 s100, v254, 63
	s_load_dwordx2 s[98:99], s[94:95], 0x18
	v_mbcnt_lo_u32_b32 v246, -1, 0
	v_mbcnt_hi_u32_b32 v246, -1, v246
	s_nop 0
	v_lshl_add_u32 v247, s100, 6, v246
	v_lshlrev_b32_e32 v247, 2, v247
	s_load_dwordx2 s[100:101], s[94:95], 0x20
	s_waitcnt lgkmcnt(0)
	global_load_dword v248, v247, s[98:99]
	global_load_dword v249, v247, s[100:101]
	v_readlane_b32 s0, v252, 6
	v_readlane_b32 s1, v252, 7
	s_andn2_b64 vcc, exec, s[0:1]
	s_mov_b64 s[26:27], 0
	v_cndmask_b32_e64 v1, 0, 1, s[0:1]
	v_cmp_ne_u32_e64 s[36:37], 1, v1
	s_cbranch_vccnz .LBB0_165
	v_mbcnt_lo_u32_b32 v1, -1, 0
	v_mbcnt_hi_u32_b32 v1, -1, v1
	s_nop 0
	v_cmp_eq_u32_e32 vcc, 0, v1
	s_and_b64 s[26:27], vcc, exec

.LBB0_168:
	s_or_b64 exec, exec, s[24:25]
	v_readlane_b32 s0, v252, 13
	v_readlane_b32 s1, v252, 14
	s_mov_b64 s[24:25], -1
	s_and_b64 vcc, exec, s[0:1]
	s_cbranch_vccz .LBB0_313
	s_mov_b64 s[24:25], s[94:95]
	v_mbcnt_lo_u32_b32 v228, -1, 0
	v_mbcnt_hi_u32_b32 v228, -1, v228
	v_readlane_b32 s0, v252, 3
	s_mov_b64 s[26:27], s[94:95]
	v_readlane_b32 s28, v254, 63
	v_readlane_b32 s29, v255, 0
	s_nop 0
	v_lshl_add_u32 v2, s28, 6, v228
	v_ashrrev_i32_e32 v3, 31, v2
	v_lshlrev_b64 v[2:3], 2, v[2:3]
	s_waitcnt lgkmcnt(0)
	v_lshl_add_u64 v[4:5], s[26:27], 0, v[2:3]
	s_mov_b64 s[26:27], s[94:95]
	v_mov_b32_e32 v1, v248
	v_lshlrev_b32_e32 v5, 2, v228
	v_xor_b32_e32 v6, 4, v5
	s_waitcnt lgkmcnt(0)
	v_lshl_add_u64 v[2:3], s[26:27], 0, v[2:3]
	v_mov_b32_e32 v2, v249
	v_readlane_b32 s26, v252, 28
	v_readlane_b32 s27, v252, 29
	s_andn2_b64 vcc, exec, s[26:27]
	s_waitcnt vmcnt(0)
	v_and_b32_e32 v4, 0x7fffffff, v1
	ds_bpermute_b32 v4, v6, v4
	v_max_f32_e64 v1, |v1|, |v1|
	s_waitcnt lgkmcnt(0)
	v_max_f32_e32 v4, v4, v4
	v_max_f32_e32 v1, v1, v4
	v_and_b32_e32 v3, 0x7fffffff, v2
	ds_bpermute_b32 v3, v6, v3
	v_max_f32_e64 v2, |v2|, |v2|
	s_waitcnt lgkmcnt(0)
	v_max_f32_e32 v3, v3, v3
	v_max_f32_e32 v2, v2, v3
	v_xor_b32_e32 v3, 8, v5
	ds_bpermute_b32 v4, v3, v1
	ds_bpermute_b32 v3, v3, v2
	s_waitcnt lgkmcnt(1)
	v_max_f32_e32 v4, v4, v4
	s_waitcnt lgkmcnt(0)
	v_max_f32_e32 v3, v3, v3
	v_max_f32_e32 v1, v1, v4
	v_max_f32_e32 v2, v2, v3
	v_xor_b32_e32 v3, 16, v5
	ds_bpermute_b32 v4, v3, v1
	ds_bpermute_b32 v3, v3, v2
	s_waitcnt lgkmcnt(1)
	v_max_f32_e32 v4, v4, v4
	s_waitcnt lgkmcnt(0)
	v_max_f32_e32 v3, v3, v3
	v_max_f32_e32 v1, v1, v4
	v_max_f32_e32 v2, v2, v3
	v_xor_b32_e32 v3, 32, v5
	ds_bpermute_b32 v4, v3, v1
	ds_bpermute_b32 v3, v3, v2
	s_waitcnt lgkmcnt(1)
	v_max_f32_e32 v4, v4, v4
	s_waitcnt lgkmcnt(0)
	v_max_f32_e32 v3, v3, v3
	v_max_f32_e32 v1, v1, v4
	v_max_f32_e32 v2, v2, v3
	v_xor_b32_e32 v3, 64, v5
	ds_bpermute_b32 v4, v3, v1
	ds_bpermute_b32 v3, v3, v2
	s_waitcnt lgkmcnt(1)
	v_max_f32_e32 v4, v4, v4
	s_waitcnt lgkmcnt(0)
	v_max_f32_e32 v3, v3, v3
	v_max_f32_e32 v1, v1, v4
	v_max_f32_e32 v2, v2, v3
	v_xor_b32_e32 v4, 0x80, v5
	ds_bpermute_b32 v3, v4, v1
	ds_bpermute_b32 v4, v4, v2
	s_cbranch_vccnz .LBB0_312
	s_load_dwordx2 s[24:25], s[24:25], 0xb0
	s_waitcnt lgkmcnt(0)
	v_max_f32_e32 v3, v3, v3
	v_max_f32_e32 v1, v1, v1
	v_max_f32_e32 v4, v4, v4
	v_max_f32_e32 v2, v2, v2
	s_add_u32 s40, s24, 0x1c00000
	s_addc_u32 s41, s25, 0
	s_add_u32 s43, s24, 0x3c00000
	v_max_f32_e32 v1, v1, v3
	s_addc_u32 s48, s25, 0
	v_max_f32_e32 v2, v2, v4
	v_mul_f32_e32 v1, 0x41000000, v1
	s_lshl_b32 s54, s0, 6
	s_mul_i32 s1, s0, 0x2400
	v_fmaak_f32 v1, v2, v1, 0x3e800000
	s_and_b32 s55, s0, 3
	s_and_b32 s56, s54, 0xffffff00
	s_add_i32 s49, s1, 0
	s_lshl_b32 s57, s0, 1
	v_mul_f32_e32 v196, 0xbfb8aa3b, v1
	s_or_b32 s0, s56, s55
	s_add_i32 s49, s49, 0x10800
	s_and_b32 s58, s57, 6
	v_mov_b32_e32 v197, v196
	v_mov_b32_e32 v198, v196
	v_mov_b32_e32 v199, v196
	v_mov_b32_e32 v200, v196
	v_mov_b32_e32 v201, v196
	v_mov_b32_e32 v202, v196
	v_mov_b32_e32 v203, v196
	v_mov_b32_e32 v204, v196
	v_mov_b32_e32 v205, v196
	v_mov_b32_e32 v206, v196
	v_mov_b32_e32 v207, v196
	v_mov_b32_e32 v208, v196
	v_mov_b32_e32 v209, v196
	v_mov_b32_e32 v210, v196
	v_mov_b32_e32 v211, v196
	v_mov_b32_e32 v212, v196
	v_mov_b32_e32 v213, v196
	s_sub_i32 s59, s0, 64
	s_add_i32 s60, s57, 0xffffff00
	s_add_i32 s61, s57, 0xffffff01
	v_readlane_b32 s62, v253, 52
	v_readlane_b32 s63, v252, 27
	s_branch .LBB0_172
